# adds (on v132): attention unit prologue issues the 14 K/V ring LDS-DMA loads before waiting on the Q/K-self loads; self-score chain moved behind with vmcnt+14
# speedup vs baseline: 1.0055x; 1.0011x over previous
; __device__ __forceinline__ float bf_lo(unsigned u) { return __uint_as_float(u << 16); }
; __device__ __forceinline__ float bf_hi(unsigned u) { return __uint_as_float(u & 0xffff0000u); }
; template <bool STORE> __device__ __forceinline__ void attn_unit(LAS unsigned char* lds, bf16_t* Q, const bf16_t* Kg, const bf16_t* VT, const float* subg, float lam, float outscale, int unit, const int wave_s) {
;     ...
;     const int bh = unit >> 4, qb = unit & 15, b = bh >> 3, h = bh & 7, map = wid >> 2;
;     const int qrow0 = qb * 128 + 32 * (wid & 3);
;     const int td = qrow0 >> 6;
;     bf16x8 qf[4];
;     { const bf16_t* Qp = Q + (size_t)(b * SEQ + qrow0 + q) * DM + h * 128 + map * 64 + 8 * hi;
; #pragma unroll
;       for (int d0 = 0; d0 < 4; ++d0) qf[d0] = *(const bf16x8*)(Qp + 16 * d0); }
;     const float sl = __int_as_float(__builtin_amdgcn_readfirstlane(__float_as_int(exp2f(-(float)(h + 1)) * LOG2E)));
;     float sself;
;     { const bf16_t* Kp = Kg + (size_t)(b * SEQ + qrow0 + q) * DM + h * 128 + map * 64 + 8 * hi; float a = 0.f;
; #pragma unroll
;       for (int d0 = 0; d0 < 4; ++d0) { const u32x4 kv = *(const u32x4*)(Kp + 16 * d0); const u32x4 qv = __builtin_bit_cast(u32x4, qf[d0]);
; #pragma unroll
;           for (int j = 0; j < 4; ++j) a += bf_lo(kv[j]) * bf_lo(qv[j]) + bf_hi(kv[j]) * bf_hi(qv[j]); }
;       sself = swap_add(a); }
;     const unsigned lds0 = (unsigned)(uintptr_t)lds;
;     const bf16_t* kgp; const bf16_t* vgp;
;     { const int kr = 8 * wid + (lane >> 4), kc = (lane & 15) ^ (kr & 15); kgp = Kg + (size_t)(b * SEQ + kr) * DM + h * 128 + kc * 8;
;       const int vr = 16 * wid + (lane >> 3), vc = (lane & 7) ^ ((vr >> 1) & 7); vgp = VT + (size_t)(h * 128 + vr) * T + b * SEQ + vc * 8; }
;     const int kx1 = ((((lane & 15) ^ ((8 * wid + (lane >> 4) + 4) & 15)) - ((lane & 15) ^ ((8 * wid + (lane >> 4)) & 15))) * 8) + 4 * DM;
;     const int vx1 = ((((lane & 7) ^ (((16 * wid + (lane >> 3) + 8) >> 1) & 7)) - ((lane & 7) ^ (((16 * wid + (lane >> 3)) >> 1) & 7))) * 8) + 8 * T;
;     const unsigned kdst = lds0 + wid * 2048, vdst = lds0 + AT_VOFF + wid * 2048;
;     ...
;     AT_ISSUE_K(0); AT_ISSUE_V(0); AT_ISSUE_K(1); AT_ISSUE_V(1); AT_ISSUE_K(2); AT_ISSUE_V(2); AT_ISSUE_K(3);
.LBB0_576:
	s_lshl_b32 s12, s61, 5
	s_add_i32 s16, s61, s39
	s_add_i32 s18, s12, s60
	s_and_b64 s[12:13], s[46:47], exec
	s_cselect_b32 s13, s18, s16
	s_cmpk_gt_i32 s13, 0x3ff
	s_cbranch_scc1 .LBB0_575
	v_mov_b32_e32 v0, v1
	s_lshl_b32 s12, s13, 7
	v_mbcnt_lo_u32_b32 v0, -1, v0
	s_and_b32 s12, s12, 0x780
	v_readlane_b32 s16, v253, 8
	s_lshl_b32 s18, s13, 4
	v_mbcnt_hi_u32_b32 v219, -1, v0
	s_or_b32 s12, s12, s16
	s_and_b32 s34, s18, 0xfffff800
	v_and_b32_e32 v3, 31, v219
	s_or_b32 s62, s12, s34
	v_or_b32_e32 v4, s62, v3
	v_ashrrev_i32_e32 v5, 31, v4
	s_bfe_u32 s19, s13, 0x30004
	v_lshlrev_b64 v[4:5], 11, v[4:5]
	v_lshl_add_u64 v[6:7], s[48:49], 0, v[4:5]
	s_lshl_b32 s16, s19, 8
	v_readlane_b32 s13, v253, 6
	v_lshl_add_u64 v[4:5], s[50:51], 0, v[4:5]
	v_bfe_u32 v2, v219, 5, 1
	s_lshl_b32 s20, s13, 1
	s_mov_b32 s21, s17
	v_lshl_add_u64 v[4:5], v[4:5], 0, s[16:17]
	v_lshl_add_u64 v[6:7], v[6:7], 0, s[16:17]
	v_lshlrev_b32_e32 v0, 4, v2
	v_lshl_add_u64 v[4:5], v[4:5], 0, s[20:21]
	v_lshl_add_u64 v[6:7], v[6:7], 0, s[20:21]
	v_lshl_add_u64 v[18:19], v[4:5], 0, v[0:1]
	v_lshl_add_u64 v[16:17], v[6:7], 0, v[0:1]
	global_load_dwordx4 v[4:7], v[18:19], off
	global_load_dwordx4 v[144:147], v[16:17], off
	global_load_dwordx4 v[8:11], v[18:19], off offset:32
	global_load_dwordx4 v[148:151], v[16:17], off offset:32
	global_load_dwordx4 v[12:15], v[18:19], off offset:64
	global_load_dwordx4 v[152:155], v[16:17], off offset:64
	global_load_dwordx4 v[156:159], v[16:17], off offset:96
	s_nop 0
	global_load_dwordx4 v[16:19], v[18:19], off offset:96
	s_add_i32 s13, s19, 1
	v_cvt_f32_ubyte0_e32 v0, s13
	s_mov_b32 s13, 0x42fc0000
	v_cmp_lt_f32_e32 vcc, s13, v0
	v_mov_b32_e32 v20, 0x42800000
	s_lshl_b32 s63, s19, 7
	v_cndmask_b32_e32 v20, 0, v20, vcc
	v_sub_f32_e32 v0, v20, v0
	v_exp_f32_e32 v0, v0
	s_and_b64 s[20:21], vcc, exec
	s_cselect_b32 s13, 0xffffffc0, 0
	v_bfe_u32 v216, v219, 4, 2
	v_ldexp_f32 v0, v0, s13
	v_bfe_u32 v218, v219, 3, 3
	v_readfirstlane_b32 s13, v0
	v_mov_b32_e32 v179, v1
	v_bitop3_b32 v217, v216, v219, 7 bitop3:0x78
	s_ashr_i32 s35, s34, 31
	v_mov_b32_e32 v171, v1
	v_mov_b32_e32 v173, v1
	s_mov_b64 s[20:21], 0x20000
	v_mov_b32_e32 v102, 0x3fb8aa3b
	v_mul_f32_e32 v166, s13, v102
	v_mov_b32_e32 v101, 0
	v_readlane_b32 s13, v253, 23
	v_and_b32_e32 v111, 15, v219
	v_and_b32_e32 v108, 7, v219
	v_or_b32_e32 v100, s13, v216
	v_add_u32_e32 v104, s34, v100
	v_ashrrev_i32_e32 v105, 31, v104
	v_bitop3_b32 v106, v216, 11, s13 bitop3:0xc8
	v_lshlrev_b64 v[104:105], 11, v[104:105]
	v_readlane_b32 s13, v253, 29
	v_bitop3_b32 v107, v100, v111, 11 bitop3:0x6c
	v_lshl_add_u64 v[104:105], s[50:51], 0, v[104:105]
	s_add_i32 s19, s63, s13
	v_lshl_add_u64 v[104:105], v[104:105], 0, s[16:17]
	v_lshlrev_b32_e32 v178, 4, v107
	v_or_b32_e32 v100, s19, v218
	v_lshl_add_u64 v[180:181], v[104:105], 0, v[178:179]
	v_lshlrev_b64 v[104:105], 15, v[100:101]
	v_lshl_add_u64 v[104:105], s[52:53], 0, v[104:105]
	v_lshl_add_u64 v[104:105], s[34:35], 1, v[104:105]
	v_lshlrev_b32_e32 v100, 4, v217
	v_lshl_add_u64 v[182:183], v[104:105], 0, v[100:101]
	v_bitop3_b32 v100, v106, v111, 4 bitop3:0x36
	v_sub_u32_e32 v100, v100, v107
	v_mov_b32_e32 v104, 0x1000
	v_lshl_add_u32 v170, v100, 3, v104
	v_bitop3_b32 v100, v216, v108, 4 bitop3:0x36
	v_sub_u32_e32 v100, v100, v217
	v_mov_b32_e32 v104, 0x20000
	v_lshl_add_u32 v172, v100, 3, v104
	v_lshlrev_b64 v[104:105], 1, v[170:171]
	s_mov_b32 m0, s37
	s_nop 0
	global_load_lds_dwordx4 v[180:181], off
	v_lshl_add_u64 v[106:107], v[180:181], 0, v[104:105]
	s_add_i32 s13, s37, 0x400
	s_mov_b32 m0, s13
	s_nop 0
	global_load_lds_dwordx4 v[106:107], off
	v_lshlrev_b64 v[106:107], 1, v[172:173]
	s_mov_b32 m0, s3
	s_nop 0
	global_load_lds_dwordx4 v[182:183], off
	v_lshl_add_u64 v[108:109], v[182:183], 0, v[106:107]
	s_add_i32 s13, s37, 0x10400
	s_mov_b32 m0, s13
	s_nop 0
	global_load_lds_dwordx4 v[108:109], off
	v_lshl_add_u64 v[108:109], v[180:181], 0, s[20:21]
	s_add_i32 s13, s37, 0x4000
	s_mov_b32 m0, s13
	s_nop 0
	global_load_lds_dwordx4 v[108:109], off
	v_lshl_add_u64 v[108:109], v[108:109], 0, v[104:105]
	s_add_i32 s13, s37, 0x4400
	s_mov_b32 m0, s13
	s_nop 0
	global_load_lds_dwordx4 v[108:109], off
	v_lshl_add_u64 v[108:109], v[182:183], 0, s[22:23]
	s_add_i32 s13, s37, 0x14000
	s_mov_b32 m0, s13
	s_nop 0
	global_load_lds_dwordx4 v[108:109], off
	v_lshl_add_u64 v[108:109], v[108:109], 0, v[106:107]
	s_add_i32 s13, s37, 0x14400
	s_mov_b32 m0, s13
	s_nop 0
	global_load_lds_dwordx4 v[108:109], off
	v_lshl_add_u64 v[108:109], v[180:181], 0, s[26:27]
	s_add_i32 s13, s37, 0x8000
	s_mov_b32 m0, s13
	s_nop 0
	global_load_lds_dwordx4 v[108:109], off
	v_lshl_add_u64 v[108:109], v[108:109], 0, v[104:105]
	s_add_i32 s13, s37, 0x8400
	s_mov_b32 m0, s13
	s_nop 0
	global_load_lds_dwordx4 v[108:109], off
	v_lshl_add_u64 v[108:109], v[182:183], 0, s[24:25]
	s_add_i32 s13, s37, 0x18000
	s_mov_b32 m0, s13
	s_nop 0
	global_load_lds_dwordx4 v[108:109], off
	v_lshl_add_u64 v[106:107], v[108:109], 0, v[106:107]
	s_mov_b64 s[20:21], 0x60000
	s_add_i32 s13, s37, 0x18400
	s_mov_b32 m0, s13
	s_nop 0
	global_load_lds_dwordx4 v[106:107], off
	v_lshl_add_u64 v[106:107], v[180:181], 0, s[20:21]
	s_add_i32 s13, s37, 0xc000
	s_mov_b32 m0, s13
	s_nop 0
	global_load_lds_dwordx4 v[106:107], off
	v_lshl_add_u64 v[104:105], v[106:107], 0, v[104:105]
	s_add_i32 s13, s37, 0xc400
	s_mov_b32 m0, s13
	s_nop 0
	global_load_lds_dwordx4 v[104:105], off
	s_waitcnt vmcnt(21)
	v_lshlrev_b32_e32 v0, 16, v4
	v_and_b32_e32 v4, 0xffff0000, v4
	s_waitcnt vmcnt(20)
; __device__ __forceinline__ float bf_lo(unsigned u) { return __uint_as_float(u << 16); }
; __device__ __forceinline__ float bf_hi(unsigned u) { return __uint_as_float(u & 0xffff0000u); }
; __device__ __forceinline__ float swap_add(float v) { auto rr = __builtin_amdgcn_permlane32_swap(__float_as_uint(v), __float_as_uint(v), false, false); return __uint_as_float(rr[0]) + __uint_as_float(rr[1]); }
; template <bool STORE> __device__ __forceinline__ void attn_unit(LAS unsigned char* lds, bf16_t* Q, const bf16_t* Kg, const bf16_t* VT, const float* subg, float lam, float outscale, int unit, const int wave_s) {
;     ...
;     { const bf16_t* Kp = Kg + (size_t)(b * SEQ + qrow0 + q) * DM + h * 128 + map * 64 + 8 * hi; float a = 0.f;
; #pragma unroll
;       for (int d0 = 0; d0 < 4; ++d0) { const u32x4 kv = *(const u32x4*)(Kp + 16 * d0); const u32x4 qv = __builtin_bit_cast(u32x4, qf[d0]);
; #pragma unroll
;           for (int j = 0; j < 4; ++j) a += bf_lo(kv[j]) * bf_lo(qv[j]) + bf_hi(kv[j]) * bf_hi(qv[j]); }
;       sself = swap_add(a); }
;     const unsigned lds0 = (unsigned)(uintptr_t)lds;
;     const bf16_t* kgp; const bf16_t* vgp;
;     { const int kr = 8 * wid + (lane >> 4), kc = (lane & 15) ^ (kr & 15); kgp = Kg + (size_t)(b * SEQ + kr) * DM + h * 128 + kc * 8;
;       const int vr = 16 * wid + (lane >> 3), vc = (lane & 7) ^ ((vr >> 1) & 7); vgp = VT + (size_t)(h * 128 + vr) * T + b * SEQ + vc * 8; }
;     const int kx1 = ((((lane & 15) ^ ((8 * wid + (lane >> 4) + 4) & 15)) - ((lane & 15) ^ ((8 * wid + (lane >> 4)) & 15))) * 8) + 4 * DM;
;     const int vx1 = ((((lane & 7) ^ (((16 * wid + (lane >> 3) + 8) >> 1) & 7)) - ((lane & 7) ^ (((16 * wid + (lane >> 3)) >> 1) & 7))) * 8) + 8 * T;
;     const unsigned kdst = lds0 + wid * 2048, vdst = lds0 + AT_VOFF + wid * 2048;
;     ...
;     AT_ISSUE_K(0); AT_ISSUE_V(0); AT_ISSUE_K(1); AT_ISSUE_V(1); AT_ISSUE_K(2); AT_ISSUE_V(2); AT_ISSUE_K(3);
;     AT_BAR(8);
;     f32x16 o[4]; o[0] = f32x16{}; o[1] = f32x16{}; o[2] = f32x16{}; o[3] = f32x16{};
;     float mref = sself + 6.0f, lsum = 0.f;
;     const int koff = q * 256 + (((map * 8 + hi) ^ (q & 15)) << 4), voff = AT_VOFF + q * 128 + ((hi ^ ((q >> 1) & 7)) << 4);
;     const float qposf = (float)(qrow0 + q - 4 * hi);
;     f32x16 x0, x1, n0, n1;
;     ...
;     { const float sg0 = td > 0 ? 1.f : 0.f;
;       AT_CINIT(0, sg0, x0, x1); AT_QK(0, x0, x1);
	v_and_b32_e32 v21, 0xffff0000, v144
	v_lshlrev_b32_e32 v20, 16, v144
	v_lshlrev_b32_e32 v22, 16, v5
	v_and_b32_e32 v5, 0xffff0000, v5
	v_and_b32_e32 v24, 0xffff0000, v145
	v_mul_f32_e32 v4, v21, v4
	v_lshlrev_b32_e32 v23, 16, v145
	v_lshlrev_b32_e32 v25, 16, v6
	v_and_b32_e32 v6, 0xffff0000, v6
	v_and_b32_e32 v27, 0xffff0000, v146
	v_mul_f32_e32 v5, v24, v5
	v_fmac_f32_e32 v4, v20, v0
	v_lshlrev_b32_e32 v26, 16, v146
	v_lshlrev_b32_e32 v28, 16, v7
	v_and_b32_e32 v7, 0xffff0000, v7
	v_and_b32_e32 v30, 0xffff0000, v147
	v_mul_f32_e32 v6, v27, v6
	v_fmac_f32_e32 v5, v23, v22
	v_add_f32_e32 v0, 0, v4
	v_lshlrev_b32_e32 v29, 16, v147
	s_waitcnt vmcnt(19)
	v_lshlrev_b32_e32 v31, 16, v8
	v_and_b32_e32 v8, 0xffff0000, v8
	s_waitcnt vmcnt(18)
	v_and_b32_e32 v33, 0xffff0000, v148
	v_mul_f32_e32 v7, v30, v7
	v_fmac_f32_e32 v6, v26, v25
	v_add_f32_e32 v0, v5, v0
	v_lshlrev_b32_e32 v32, 16, v148
	v_lshlrev_b32_e32 v34, 16, v9
	v_and_b32_e32 v9, 0xffff0000, v9
	v_and_b32_e32 v36, 0xffff0000, v149
	v_mul_f32_e32 v8, v33, v8
	v_fmac_f32_e32 v7, v29, v28
	v_add_f32_e32 v0, v6, v0
	v_lshlrev_b32_e32 v35, 16, v149
	v_lshlrev_b32_e32 v37, 16, v10
	v_and_b32_e32 v10, 0xffff0000, v10
	v_and_b32_e32 v39, 0xffff0000, v150
	v_mul_f32_e32 v9, v36, v9
	v_fmac_f32_e32 v8, v32, v31
	v_add_f32_e32 v0, v7, v0
	v_lshlrev_b32_e32 v38, 16, v150
	v_lshlrev_b32_e32 v40, 16, v11
	v_and_b32_e32 v11, 0xffff0000, v11
	v_and_b32_e32 v42, 0xffff0000, v151
	v_mul_f32_e32 v10, v39, v10
	v_fmac_f32_e32 v9, v35, v34
	v_add_f32_e32 v0, v8, v0
	v_lshlrev_b32_e32 v41, 16, v151
	v_mul_f32_e32 v11, v42, v11
	v_fmac_f32_e32 v10, v38, v37
	v_add_f32_e32 v0, v9, v0
	s_waitcnt vmcnt(17)
	v_and_b32_e32 v6, 0xffff0000, v12
	s_waitcnt vmcnt(16)
	v_and_b32_e32 v7, 0xffff0000, v152
	v_fmac_f32_e32 v11, v41, v40
	v_add_f32_e32 v0, v10, v0
	v_lshlrev_b32_e32 v4, 16, v12
	v_lshlrev_b32_e32 v5, 16, v152
	v_mul_f32_e32 v6, v7, v6
	v_add_f32_e32 v0, v11, v0
	v_fmac_f32_e32 v6, v5, v4
	v_add_f32_e32 v0, v6, v0
	v_and_b32_e32 v6, 0xffff0000, v13
	v_and_b32_e32 v7, 0xffff0000, v153
	v_lshlrev_b32_e32 v4, 16, v13
	v_lshlrev_b32_e32 v5, 16, v153
	v_mul_f32_e32 v6, v7, v6
	v_fmac_f32_e32 v6, v5, v4
	v_and_b32_e32 v9, 0xffff0000, v15
	v_and_b32_e32 v8, 0xffff0000, v14
	v_and_b32_e32 v11, 0xffff0000, v155
	v_and_b32_e32 v10, 0xffff0000, v154
	v_add_f32_e32 v0, v6, v0
	v_lshlrev_b32_e32 v5, 16, v15
	v_lshlrev_b32_e32 v4, 16, v14
	v_lshlrev_b32_e32 v7, 16, v155
	v_lshlrev_b32_e32 v6, 16, v154
	v_pk_mul_f32 v[8:9], v[10:11], v[8:9]
	s_waitcnt vmcnt(15)
	v_and_b32_e32 v11, 0xffff0000, v157
	v_pk_fma_f32 v[4:5], v[6:7], v[4:5], v[8:9]
	s_waitcnt vmcnt(14)
	v_and_b32_e32 v9, 0xffff0000, v17
	v_add_f32_e32 v0, v4, v0
	v_and_b32_e32 v8, 0xffff0000, v16
	v_and_b32_e32 v10, 0xffff0000, v156
	v_add_f32_e32 v0, v5, v0
	v_lshlrev_b32_e32 v5, 16, v17
	v_lshlrev_b32_e32 v4, 16, v16
	v_lshlrev_b32_e32 v7, 16, v157
	v_lshlrev_b32_e32 v6, 16, v156
	v_pk_mul_f32 v[8:9], v[10:11], v[8:9]
	v_and_b32_e32 v11, 0xffff0000, v159
	v_pk_fma_f32 v[4:5], v[6:7], v[4:5], v[8:9]
	v_and_b32_e32 v9, 0xffff0000, v19
	v_add_f32_e32 v0, v4, v0
	v_and_b32_e32 v8, 0xffff0000, v18
	v_and_b32_e32 v10, 0xffff0000, v158
	v_add_f32_e32 v0, v5, v0
	v_lshlrev_b32_e32 v5, 16, v19
	v_lshlrev_b32_e32 v4, 16, v18
	v_lshlrev_b32_e32 v7, 16, v159
	v_lshlrev_b32_e32 v6, 16, v158
	v_pk_mul_f32 v[8:9], v[10:11], v[8:9]
	v_pk_fma_f32 v[4:5], v[6:7], v[4:5], v[8:9]
	v_add_f32_e32 v0, v4, v0
	v_add_f32_e32 v0, v5, v0
	v_mov_b32_e32 v4, v0
	s_nop 1
	v_permlane32_swap_b32_e32 v0, v4
	v_add_f32_e32 v10, v0, v4
	v_add_f32_e32 v169, 0x40c00000, v10
	v_and_b32_e32 v11, 15, v219
	v_or_b32_e32 v0, s12, v3
	v_lshlrev_b32_e32 v4, 2, v2
	v_sub_u32_e32 v0, v0, v4
	s_cmp_gt_u32 s12, 63
	v_cvt_f32_i32_e32 v205, v0
	s_cselect_b64 s[40:41], -1, 0
	s_cmp_lt_u32 s12, 64
	s_cselect_b64 s[20:21], -1, 0
	v_cndmask_b32_e64 v4, 1.0, 0, s[20:21]
	v_mul_f32_e32 v4, v4, v166
	v_mul_f32_e64 v5, -v205, v4
	v_mov_b32_e32 v168, v4
	v_add_f32_e32 v6, v4, v168
	v_sub_f32_e32 v8, v4, v168
	v_sub_f32_e32 v9, v5, v169
	v_readlane_b32 s13, v253, 24
	v_mov_b32_e32 v7, v9
	s_waitcnt vmcnt(8) lgkmcnt(0)
	s_barrier
	v_mov_b32_e32 v96, v9
	v_bitop3_b32 v38, v2, v11, s13 bitop3:0x36
	v_add_f32_e32 v10, v6, v6
	v_add_f32_e32 v11, v7, v7
	s_and_b64 vcc, exec, s[40:41]
	v_pk_fma_f32 v[12:13], v[6:7], 2.0, v[10:11] op_sel_hi:[1,0,1]
	s_nop 0
	v_pk_fma_f32 v[10:11], v[10:11], 2.0, v[12:13] op_sel_hi:[1,0,1]
	v_mov_b32_e32 v19, v12
	v_pk_fma_f32 v[10:11], v[12:13], 2.0, v[10:11] op_sel_hi:[1,0,1]
	s_nop 0
	v_mov_b32_e32 v5, v10
	v_add_f32_e32 v10, v4, v6
	v_add_f32_e32 v11, v5, v7
	v_mov_b32_e32 v5, v6
	v_pk_mov_b32 v[16:17], v[10:11], v[12:13] op_sel:[1,0]
	v_mov_b32_e32 v18, v10
	v_add_f32_e32 v16, v16, v10
	v_add_f32_e32 v17, v17, v11
	v_add_f32_e32 v12, v18, v9
	v_add_f32_e32 v13, v19, v9
	v_add_f32_e32 v26, v18, v17
	v_add_f32_e32 v27, v19, v17
	v_add_f32_e32 v24, v18, v13
	v_add_f32_e32 v25, v19, v13
	v_add_f32_e32 v6, v4, v9
	v_add_f32_e32 v7, v5, v9
	v_add_f32_e32 v32, v18, v25
	v_add_f32_e32 v33, v19, v25
	v_add_f32_e32 v18, v18, v27
	v_add_f32_e32 v19, v19, v27
	v_add_f32_e32 v14, v4, v11
	v_add_f32_e32 v15, v5, v11
	v_add_f32_e32 v20, v4, v13
	v_add_f32_e32 v21, v5, v13
	v_add_f32_e32 v22, v4, v17
	v_add_f32_e32 v23, v5, v17
	v_add_f32_e32 v28, v4, v25
	v_add_f32_e32 v29, v5, v25
	v_add_f32_e32 v30, v4, v27
	v_add_f32_e32 v31, v5, v27
	v_add_f32_e32 v34, v4, v33
	v_add_f32_e32 v35, v5, v33
	v_mov_b32_e32 v99, v12
	v_mov_b32_e32 v100, v13
	v_add_f32_e32 v12, v4, v19
	v_add_f32_e32 v13, v5, v19
	v_lshlrev_b32_e32 v4, 8, v3
	v_lshl_add_u32 v210, v38, 4, v4
	v_add_u32_e32 v208, 0, v210
	v_mov_b32_e32 v97, v6
	v_mov_b32_e32 v98, v7
	ds_read_b128 v[4:7], v208
	v_add_f32_e32 v36, v10, v33
	v_add_f32_e32 v37, v11, v32
	v_xor_b32_e32 v211, 32, v210
	v_mov_b32_e32 v101, v20
	v_mov_b32_e32 v102, v21
	v_mov_b32_e32 v103, v24
	v_mov_b32_e32 v104, v25
	v_mov_b32_e32 v105, v28
	v_mov_b32_e32 v106, v29
	v_mov_b32_e32 v107, v32
	v_mov_b32_e32 v108, v33
	v_mov_b32_e32 v109, v34
	v_mov_b32_e32 v110, v35
	v_mov_b32_e32 v111, v36
	v_add_u32_e32 v209, 0, v211
	v_add_f32_e32 v20, v10, v19
	v_add_f32_e32 v21, v11, v18
	v_mov_b32_e32 v80, v11
	ds_read_b128 v[8:11], v208 offset:8192
	s_waitcnt lgkmcnt(1)
; #define AT_DIAG(tt, c0, c1) do { const float base_ = qposf - (float)(64 * (tt)); \
;         _Pragma("unroll") for (int r = 0; r < 16; ++r) { const float cr_ = (float)((r & 3) + 8 * (r >> 2)); c0[r] -= sl * fabsf(base_ - cr_); c1[r] -= sl * fabsf(base_ - 32.f - cr_); } } while (0)
; template <bool STORE> __device__ __forceinline__ void attn_unit(LAS unsigned char* lds, bf16_t* Q, const bf16_t* Kg, const bf16_t* VT, const float* subg, float lam, float outscale, int unit, const int wave_s) {
;     ...
;     { const float sg0 = td > 0 ? 1.f : 0.f;
;       AT_CINIT(0, sg0, x0, x1); AT_QK(0, x0, x1);
;       if (td == 0) AT_DIAG(0, x0, x1);
	v_mfma_f32_32x32x16_bf16 v[96:111], v[4:7], v[144:147], v[96:111]
	ds_read_b128 v[4:7], v209
	v_mov_b32_e32 v81, v14
	v_mov_b32_e32 v82, v15
	v_mov_b32_e32 v83, v16
	v_mov_b32_e32 v84, v17
	v_mov_b32_e32 v85, v22
	v_mov_b32_e32 v86, v23
	v_mov_b32_e32 v87, v26
	v_mov_b32_e32 v88, v27
	v_mov_b32_e32 v89, v30
	v_mov_b32_e32 v90, v31
	v_mov_b32_e32 v91, v18
	v_mov_b32_e32 v92, v19
	v_mov_b32_e32 v93, v12
	v_mov_b32_e32 v94, v13
	v_mov_b32_e32 v95, v20
	s_waitcnt lgkmcnt(0)
	v_mfma_f32_32x32x16_bf16 v[96:111], v[4:7], v[148:151], v[96:111]
	ds_read_b128 v[4:7], v209 offset:8192
	v_xor_b32_e32 v212, 64, v210
	v_add_u32_e32 v206, 0, v212
	v_xor_b32_e32 v213, 0x60, v210
	v_add_u32_e32 v207, 0, v213
	v_mfma_f32_32x32x16_bf16 v[80:95], v[8:11], v[144:147], v[80:95]
	s_waitcnt lgkmcnt(0)
	v_mfma_f32_32x32x16_bf16 v[80:95], v[4:7], v[148:151], v[80:95]
	ds_read_b128 v[4:7], v206
	s_waitcnt lgkmcnt(0)
	v_mfma_f32_32x32x16_bf16 v[96:111], v[4:7], v[152:155], v[96:111]
	ds_read_b128 v[4:7], v206 offset:8192
	s_waitcnt lgkmcnt(0)
	v_mfma_f32_32x32x16_bf16 v[80:95], v[4:7], v[152:155], v[80:95]
	ds_read_b128 v[4:7], v207
	s_waitcnt lgkmcnt(0)
	v_mfma_f32_32x32x16_bf16 v[96:111], v[4:7], v[156:159], v[96:111]
	ds_read_b128 v[4:7], v207 offset:8192
	s_waitcnt lgkmcnt(0)
	v_mfma_f32_32x32x16_bf16 v[80:95], v[4:7], v[156:159], v[80:95]
	s_cbranch_vccnz .LBB0_579
	v_add_u32_e32 v4, -1, v0
	v_cvt_f32_i32_e32 v5, v4
	v_add_u32_e32 v4, -3, v0
	v_cvt_f32_i32_e32 v7, v4
	v_add_u32_e32 v4, -9, v0
	v_cvt_f32_i32_e32 v9, v4
	v_add_u32_e32 v4, -11, v0
	v_cvt_f32_i32_e32 v11, v4
	v_add_u32_e32 v4, -16, v0
	v_cvt_f32_i32_e32 v14, v4
	v_subrev_u32_e32 v4, 19, v0
	v_subrev_u32_e32 v13, 18, v0
	v_cvt_f32_i32_e32 v16, v13
	v_cvt_f32_i32_e32 v15, v4
	v_subrev_u32_e32 v4, 25, v0
	v_subrev_u32_e32 v13, 24, v0
	v_add_u32_e32 v6, -2, v0
	v_add_u32_e32 v8, -8, v0
	v_add_u32_e32 v10, -10, v0
	v_subrev_u32_e32 v12, 17, v0
	v_cvt_f32_i32_e32 v18, v13
	v_cvt_f32_i32_e32 v17, v4
	v_subrev_u32_e32 v4, 27, v0
	v_subrev_u32_e32 v13, 26, v0
	v_cvt_f32_i32_e32 v6, v6
	v_cvt_f32_i32_e32 v8, v8
	v_cvt_f32_i32_e32 v10, v10
	v_cvt_f32_i32_e32 v12, v12
	v_cvt_f32_i32_e32 v20, v13
	v_cvt_f32_i32_e32 v19, v4
	v_and_b32_e32 v4, 0x7fffffff, v205
	v_and_b32_e32 v5, 0x7fffffff, v5
	v_and_b32_e32 v7, 0x7fffffff, v7
	v_and_b32_e32 v6, 0x7fffffff, v6
	v_and_b32_e32 v9, 0x7fffffff, v9
	v_and_b32_e32 v8, 0x7fffffff, v8
	v_and_b32_e32 v11, 0x7fffffff, v11
	v_and_b32_e32 v10, 0x7fffffff, v10
	v_and_b32_e32 v13, 0x7fffffff, v12
	v_and_b32_e32 v12, 0x7fffffff, v14
	v_and_b32_e32 v15, 0x7fffffff, v15
	v_and_b32_e32 v14, 0x7fffffff, v16
	v_and_b32_e32 v17, 0x7fffffff, v17
	v_and_b32_e32 v16, 0x7fffffff, v18
	v_and_b32_e32 v19, 0x7fffffff, v19
	v_and_b32_e32 v18, 0x7fffffff, v20
	v_pk_fma_f32 v[110:111], v[166:167], v[18:19], v[110:111] op_sel_hi:[0,1,1] neg_lo:[1,0,0] neg_hi:[1,0,0]
	v_pk_fma_f32 v[108:109], v[166:167], v[16:17], v[108:109] op_sel_hi:[0,1,1] neg_lo:[1,0,0] neg_hi:[1,0,0]
	v_pk_fma_f32 v[106:107], v[166:167], v[14:15], v[106:107] op_sel_hi:[0,1,1] neg_lo:[1,0,0] neg_hi:[1,0,0]
	v_pk_fma_f32 v[104:105], v[166:167], v[12:13], v[104:105] op_sel_hi:[0,1,1] neg_lo:[1,0,0] neg_hi:[1,0,0]
	v_pk_fma_f32 v[102:103], v[166:167], v[10:11], v[102:103] op_sel_hi:[0,1,1] neg_lo:[1,0,0] neg_hi:[1,0,0]
	v_pk_fma_f32 v[100:101], v[166:167], v[8:9], v[100:101] op_sel_hi:[0,1,1] neg_lo:[1,0,0] neg_hi:[1,0,0]
	v_pk_fma_f32 v[98:99], v[166:167], v[6:7], v[98:99] op_sel_hi:[0,1,1] neg_lo:[1,0,0] neg_hi:[1,0,0]
	v_pk_fma_f32 v[96:97], v[166:167], v[4:5], v[96:97] op_sel_hi:[0,1,1] neg_lo:[1,0,0] neg_hi:[1,0,0]
	v_subrev_u32_e32 v4, 33, v0
	v_subrev_u32_e32 v5, 32, v0
	v_subrev_u32_e32 v6, 35, v0
	v_subrev_u32_e32 v7, 34, v0
	v_subrev_u32_e32 v8, 41, v0
	v_subrev_u32_e32 v9, 40, v0
	v_subrev_u32_e32 v10, 43, v0
	v_subrev_u32_e32 v11, 42, v0
	v_subrev_u32_e32 v12, 49, v0
	v_subrev_u32_e32 v13, 48, v0
	v_subrev_u32_e32 v14, 51, v0
	v_subrev_u32_e32 v15, 50, v0
	v_subrev_u32_e32 v16, 57, v0
	v_subrev_u32_e32 v17, 56, v0
	v_subrev_u32_e32 v18, 59, v0
	v_subrev_u32_e32 v0, 58, v0
	v_cvt_f32_i32_e32 v0, v0
	v_cvt_f32_i32_e32 v18, v18
	v_cvt_f32_i32_e32 v19, v17
	v_cvt_f32_i32_e32 v16, v16
	v_cvt_f32_i32_e32 v17, v15
	v_cvt_f32_i32_e32 v14, v14
	v_cvt_f32_i32_e32 v15, v13
	v_cvt_f32_i32_e32 v12, v12
	v_cvt_f32_i32_e32 v13, v11
	v_cvt_f32_i32_e32 v10, v10
	v_cvt_f32_i32_e32 v11, v9
	v_cvt_f32_i32_e32 v8, v8
	v_cvt_f32_i32_e32 v4, v4
	v_cvt_f32_i32_e32 v9, v5
	v_cvt_f32_i32_e32 v6, v6
	v_cvt_f32_i32_e32 v20, v7
	v_and_b32_e32 v5, 0x7fffffff, v4
	v_and_b32_e32 v4, 0x7fffffff, v9
	v_and_b32_e32 v7, 0x7fffffff, v6
	v_and_b32_e32 v6, 0x7fffffff, v20
	v_and_b32_e32 v9, 0x7fffffff, v8
	v_and_b32_e32 v8, 0x7fffffff, v11
	v_and_b32_e32 v11, 0x7fffffff, v10
	v_and_b32_e32 v10, 0x7fffffff, v13
	v_and_b32_e32 v13, 0x7fffffff, v12
	v_and_b32_e32 v12, 0x7fffffff, v15
	v_and_b32_e32 v15, 0x7fffffff, v14
	v_and_b32_e32 v14, 0x7fffffff, v17
	v_and_b32_e32 v17, 0x7fffffff, v16
	v_and_b32_e32 v16, 0x7fffffff, v19
	v_and_b32_e32 v19, 0x7fffffff, v18
	v_and_b32_e32 v18, 0x7fffffff, v0
	v_pk_fma_f32 v[94:95], v[166:167], v[18:19], v[94:95] op_sel_hi:[0,1,1] neg_lo:[1,0,0] neg_hi:[1,0,0]
	v_pk_fma_f32 v[92:93], v[166:167], v[16:17], v[92:93] op_sel_hi:[0,1,1] neg_lo:[1,0,0] neg_hi:[1,0,0]
	v_pk_fma_f32 v[90:91], v[166:167], v[14:15], v[90:91] op_sel_hi:[0,1,1] neg_lo:[1,0,0] neg_hi:[1,0,0]
	v_pk_fma_f32 v[88:89], v[166:167], v[12:13], v[88:89] op_sel_hi:[0,1,1] neg_lo:[1,0,0] neg_hi:[1,0,0]
	v_pk_fma_f32 v[86:87], v[166:167], v[10:11], v[86:87] op_sel_hi:[0,1,1] neg_lo:[1,0,0] neg_hi:[1,0,0]
	v_pk_fma_f32 v[84:85], v[166:167], v[8:9], v[84:85] op_sel_hi:[0,1,1] neg_lo:[1,0,0] neg_hi:[1,0,0]
	v_pk_fma_f32 v[82:83], v[166:167], v[6:7], v[82:83] op_sel_hi:[0,1,1] neg_lo:[1,0,0] neg_hi:[1,0,0]
	v_pk_fma_f32 v[80:81], v[166:167], v[4:5], v[80:81] op_sel_hi:[0,1,1] neg_lo:[1,0,0] neg_hi:[1,0,0]
